# speedup vs baseline: 1.0025x; 1.0025x over previous
; __global__ void __launch_bounds__(256, 2) fwd_kernel(Params p) {
;     ...
;                 if (p.phase_lo < p.phase_hi) {
;                     unsigned* ctr = (unsigned*)(pq.ws + OFF_ctr) + l;
;                     for (;;) {
;                         if (threadIdx.x == 0) xb_st[2] = atomicAdd(ctr, 1u);
;                         __syncthreads();
;                         const int job = (int)xb_st[2];
;                         __syncthreads();
.LBB0_945:
	s_mov_b64 s[0:1], exec
	v_readlane_b32 s4, v251, 17
	v_readlane_b32 s5, v251, 18
	s_and_b64 s[4:5], s[0:1], s[4:5]
	s_mov_b64 exec, s[4:5]
	s_cbranch_execz .LBB0_947
	v_readlane_b32 s4, v254, 57
	v_readlane_b32 s5, v254, 58
	s_nop 1
	v_mov_b64_e32 v[0:1], s[4:5]
	flat_atomic_add v0, v[0:1], v190 sc0
	v_readlane_b32 s4, v252, 25
	s_nop 1
	v_mov_b32_e32 v1, s4
	s_waitcnt vmcnt(0) lgkmcnt(0)
	ds_write_b32 v1, v0
